# gate_item odd layers: 4 tokens' row loads plus ssd_norm/ssd_d requested once before the token loop (on top of v37)
# baseline (speedup 1.0000x reference)
.Lgate_odd_pre:
	v_mov_b64_e32 v[114:115], s[30:31]
	v_mov_b32_e32 v116, v43
	v_ashrrev_i32_e32 v117, 31, v43
	v_mad_i64_i32 v[114:115], s[50:51], v43, s33, v[114:115]
	v_lshlrev_b64 v[116:117], 11, v[116:117]
	s_mov_b64 s[52:53], 0x1000
	v_lshl_add_u64 v[114:115], v[114:115], 0, v[16:17]
	v_lshl_add_u64 v[116:117], v[26:27], 0, v[116:117]
	global_load_dwordx4 v[108:111], v[30:31], off
	global_load_dwordx4 v[104:107], v[30:31], off offset:16
	global_load_dword v102, v[28:29], off
	global_load_dwordx4 v[12:15], v[114:115], off offset:1024
	global_load_dwordx4 v[8:11], v[114:115], off offset:2048
	global_load_dwordx4 v[0:3], v[114:115], off
	global_load_dwordx4 v[4:7], v[116:117], off
	v_lshl_add_u64 v[118:119], v[116:117], 0, s[52:53]
	s_mov_b64 s[52:53], 0x1800
	v_lshl_add_u64 v[114:115], v[114:115], 0, s[52:53]
	global_load_dwordx4 v[66:69], v[114:115], off offset:1024
	global_load_dwordx4 v[62:65], v[114:115], off offset:2048
	global_load_dwordx4 v[54:57], v[114:115], off
	global_load_dwordx4 v[58:61], v[116:117], off offset:2048
	v_lshl_add_u64 v[114:115], v[114:115], 0, s[52:53]
	global_load_dwordx4 v[82:85], v[114:115], off offset:1024
	global_load_dwordx4 v[78:81], v[114:115], off offset:2048
	global_load_dwordx4 v[70:73], v[114:115], off
	global_load_dwordx4 v[74:77], v[118:119], off
	v_lshl_add_u64 v[114:115], v[114:115], 0, s[52:53]
	global_load_dwordx4 v[98:101], v[114:115], off offset:1024
	global_load_dwordx4 v[94:97], v[114:115], off offset:2048
	global_load_dwordx4 v[86:89], v[114:115], off
	global_load_dwordx4 v[90:93], v[118:119], off offset:2048
	s_branch .LBB0_883

.LBB0_883:
	s_mov_b64 s[50:51], -1
	s_and_b64 vcc, exec, s[10:11]
	s_cbranch_vccz .LBB0_885
	v_add_u32_e32 v112, s25, v43
	v_mov_b64_e32 v[114:115], s[30:31]
	s_nop 0
	v_mad_i64_i32 v[114:115], s[50:51], v112, s33, v[114:115]
	s_nop 0
	v_lshl_add_u64 v[36:37], v[114:115], 0, v[16:17]
	v_cmp_lt_i32_e32 vcc, v221, v220
	s_waitcnt vmcnt(12)
	v_mov_b32_e32 v42, v102
	v_and_b32_e32 v19, 0xffff0000, v12
	v_cndmask_b32_e32 v18, v218, v221, vcc
	v_cmp_lt_i32_e32 vcc, v222, v220
	v_and_b32_e32 v21, 0xffff0000, v8
	v_lshlrev_b32_e32 v20, 16, v8
	v_and_b32_e32 v8, 0xffff0000, v0
	v_lshlrev_b32_e32 v0, 16, v0
	v_lshlrev_b32_e32 v49, 2, v18
	v_cndmask_b32_e32 v18, v218, v222, vcc
	v_cmp_lt_i32_e32 vcc, v223, v220
	v_and_b32_e32 v23, 0xffff0000, v4
	v_lshlrev_b32_e32 v22, 16, v4
	v_mul_f32_e32 v4, 0xbfb8aa3b, v0
	v_lshlrev_b32_e32 v48, 2, v18
	v_cndmask_b32_e32 v18, v218, v223, vcc
	v_cmp_lt_i32_e32 vcc, v224, v220
	v_exp_f32_e32 v24, v4
	v_mul_f32_e32 v4, 0xbfb8aa3b, v8
	v_lshlrev_b32_e32 v47, 2, v18
	v_cndmask_b32_e32 v18, v218, v224, vcc
	v_cmp_lt_i32_e32 vcc, v225, v220
	v_exp_f32_e32 v25, v4
	v_lshlrev_b32_e32 v46, 2, v18
	v_cndmask_b32_e32 v18, v218, v225, vcc
	v_cmp_lt_i32_e32 vcc, v226, v220
	v_lshlrev_b32_e32 v45, 2, v18
	v_and_b32_e32 v52, 0xffff0000, v1
	v_cndmask_b32_e32 v18, v218, v226, vcc
	v_lshlrev_b32_e32 v44, 2, v18
	v_lshlrev_b32_e32 v18, 16, v12
	v_pk_add_f32 v[18:19], v[18:19], v[20:21]
	v_pk_add_f32 v[20:21], v[24:25], 1.0 op_sel_hi:[1,0]
	v_pk_fma_f32 v[18:19], v[42:43], v[22:23], v[18:19] op_sel_hi:[0,1,1]
	v_div_scale_f32 v4, s[50:51], v21, v21, v8
	v_rcp_f32_e32 v12, v4
	v_lshlrev_b32_e32 v53, 16, v1
	v_and_b32_e32 v1, 0xffff0000, v5
	v_and_b32_e32 v51, 0xffff0000, v13
	v_fma_f32 v22, -v4, v12, 1.0
	v_fmac_f32_e32 v12, v22, v12
	v_div_scale_f32 v22, vcc, v8, v21, v8
	v_mul_f32_e32 v23, v22, v12
	v_fma_f32 v24, -v4, v23, v22
	v_fmac_f32_e32 v23, v24, v12
	v_fma_f32 v4, -v4, v23, v22
	v_div_fmas_f32 v4, v4, v12, v23
	v_div_fixup_f32 v21, v4, v21, v8
	v_div_scale_f32 v4, s[50:51], v20, v20, v0
	v_rcp_f32_e32 v8, v4
	v_lshlrev_b32_e32 v50, 16, v13
	v_and_b32_e32 v13, 0xffff0000, v9
	v_fma_f32 v12, -v4, v8, 1.0
	v_fmac_f32_e32 v8, v12, v8
	v_div_scale_f32 v12, vcc, v0, v20, v0
	v_mul_f32_e32 v22, v12, v8
	v_fma_f32 v23, -v4, v22, v12
	v_fmac_f32_e32 v22, v23, v8
	v_fma_f32 v4, -v4, v22, v12
	v_div_fmas_f32 v4, v4, v8, v22
	v_div_fixup_f32 v20, v4, v20, v0
	v_lshlrev_b32_e32 v0, 16, v5
	v_mul_f32_e32 v4, 0xbfb8aa3b, v53
	v_mul_f32_e32 v5, 0xbfb8aa3b, v52
	v_exp_f32_e32 v4, v4
	v_exp_f32_e32 v5, v5
	v_lshlrev_b32_e32 v12, 16, v9
	v_pk_add_f32 v[8:9], v[50:51], v[12:13]
	v_and_b32_e32 v51, 0xffff0000, v6
	v_pk_add_f32 v[4:5], v[4:5], 1.0 op_sel_hi:[1,0]
	v_pk_fma_f32 v[0:1], v[42:43], v[0:1], v[8:9] op_sel_hi:[0,1,1]
	v_div_scale_f32 v8, s[50:51], v5, v5, v52
	v_rcp_f32_e32 v9, v8
	v_pk_mul_f32 v[38:39], v[18:19], v[20:21]
	v_mov_b64_e32 v[18:19], v[104:105]
	v_mov_b64_e32 v[20:21], v[106:107]
	v_mov_b64_e32 v[22:23], v[108:109]
	v_mov_b64_e32 v[24:25], v[110:111]
	v_pk_mul_f32 v[40:41], v[38:39], v[38:39]
	v_fma_f32 v12, -v8, v9, 1.0
	v_fmac_f32_e32 v9, v12, v9
	v_div_scale_f32 v12, vcc, v52, v5, v52
	v_mul_f32_e32 v13, v12, v9
	v_fma_f32 v50, -v8, v13, v12
	v_fmac_f32_e32 v13, v50, v9
	v_fma_f32 v8, -v8, v13, v12
	v_div_fmas_f32 v8, v8, v9, v13
	v_div_fixup_f32 v5, v8, v5, v52
	v_div_scale_f32 v8, s[50:51], v4, v4, v53
	v_rcp_f32_e32 v9, v8
	s_nop 0
	v_fma_f32 v12, -v8, v9, 1.0
	v_fmac_f32_e32 v9, v12, v9
	v_div_scale_f32 v12, vcc, v53, v4, v53
	v_mul_f32_e32 v13, v12, v9
	v_fma_f32 v50, -v8, v13, v12
	v_fmac_f32_e32 v13, v50, v9
	v_fma_f32 v8, -v8, v13, v12
	v_div_fmas_f32 v8, v8, v9, v13
	v_and_b32_e32 v13, 0xffff0000, v10
	v_lshlrev_b32_e32 v12, 16, v10
	v_and_b32_e32 v10, 0xffff0000, v2
	v_lshlrev_b32_e32 v2, 16, v2
	v_lshlrev_b32_e32 v50, 16, v6
	v_mul_f32_e32 v6, 0xbfb8aa3b, v2
	v_exp_f32_e32 v52, v6
	v_mul_f32_e32 v6, 0xbfb8aa3b, v10
	v_div_fixup_f32 v4, v8, v4, v53
	v_exp_f32_e32 v53, v6
	v_and_b32_e32 v9, 0xffff0000, v14
	v_lshlrev_b32_e32 v8, 16, v14
	v_pk_add_f32 v[8:9], v[8:9], v[12:13]
	v_pk_add_f32 v[12:13], v[52:53], 1.0 op_sel_hi:[1,0]
	v_pk_fma_f32 v[8:9], v[42:43], v[50:51], v[8:9] op_sel_hi:[0,1,1]
	v_div_scale_f32 v6, s[50:51], v13, v13, v10
	v_rcp_f32_e32 v14, v6
	v_lshlrev_b32_e32 v53, 16, v3
	v_pk_mul_f32 v[0:1], v[0:1], v[4:5]
	v_fma_f32 v50, -v6, v14, 1.0
	v_fmac_f32_e32 v14, v50, v14
	v_div_scale_f32 v50, vcc, v10, v13, v10
	v_mul_f32_e32 v51, v50, v14
	v_fma_f32 v52, -v6, v51, v50
	v_fmac_f32_e32 v51, v52, v14
	v_fma_f32 v6, -v6, v51, v50
	v_div_fmas_f32 v6, v6, v14, v51
	v_div_fixup_f32 v13, v6, v13, v10
	v_div_scale_f32 v6, s[50:51], v12, v12, v2
	v_rcp_f32_e32 v10, v6
	v_and_b32_e32 v52, 0xffff0000, v3
	v_and_b32_e32 v3, 0xffff0000, v7
	v_pk_mul_f32 v[4:5], v[0:1], v[0:1]
	v_fma_f32 v14, -v6, v10, 1.0
	v_fmac_f32_e32 v10, v14, v10
	v_div_scale_f32 v14, vcc, v2, v12, v2
	v_mul_f32_e32 v50, v14, v10
	v_fma_f32 v51, -v6, v50, v14
	v_fmac_f32_e32 v50, v51, v10
	v_fma_f32 v6, -v6, v50, v14
	v_div_fmas_f32 v6, v6, v10, v50
	v_div_fixup_f32 v12, v6, v12, v2
	v_lshlrev_b32_e32 v2, 16, v7
	v_mul_f32_e32 v6, 0xbfb8aa3b, v53
	v_mul_f32_e32 v7, 0xbfb8aa3b, v52
	v_exp_f32_e32 v6, v6
	v_exp_f32_e32 v7, v7
	v_and_b32_e32 v51, 0xffff0000, v15
	v_lshlrev_b32_e32 v50, 16, v15
	v_and_b32_e32 v15, 0xffff0000, v11
	v_lshlrev_b32_e32 v14, 16, v11
	v_pk_add_f32 v[10:11], v[50:51], v[14:15]
	v_pk_add_f32 v[6:7], v[6:7], 1.0 op_sel_hi:[1,0]
	v_pk_fma_f32 v[2:3], v[42:43], v[2:3], v[10:11] op_sel_hi:[0,1,1]
	v_div_scale_f32 v10, s[50:51], v7, v7, v52
	v_rcp_f32_e32 v11, v10
	v_pk_mul_f32 v[8:9], v[8:9], v[12:13]
	v_fma_f32 v14, -v10, v11, 1.0
	v_fmac_f32_e32 v11, v14, v11
	v_div_scale_f32 v14, vcc, v52, v7, v52
	v_mul_f32_e32 v15, v14, v11
	v_fma_f32 v42, -v10, v15, v14
	v_fmac_f32_e32 v15, v42, v11
	v_fma_f32 v10, -v10, v15, v14
	v_div_fmas_f32 v10, v10, v11, v15
	v_div_fixup_f32 v7, v10, v7, v52
	v_div_scale_f32 v10, s[50:51], v6, v6, v53
	v_rcp_f32_e32 v11, v10
	v_pk_mul_f32 v[12:13], v[8:9], v[8:9]
	s_mov_b64 s[50:51], 0
	v_fma_f32 v14, -v10, v11, 1.0
	v_fmac_f32_e32 v11, v14, v11
	v_div_scale_f32 v14, vcc, v53, v6, v53
	v_mul_f32_e32 v15, v14, v11
	v_fma_f32 v42, -v10, v15, v14
	v_fmac_f32_e32 v15, v42, v11
	v_fma_f32 v10, -v10, v15, v14
	v_div_fmas_f32 v10, v10, v11, v15
	v_div_fixup_f32 v6, v10, v6, v53
	v_add_f32_e32 v10, v40, v41
	v_add_f32_e32 v4, v4, v10
	v_add_f32_e32 v4, v5, v4
	v_pk_mul_f32 v[6:7], v[2:3], v[6:7]
	v_add_f32_e32 v4, v12, v4
	v_pk_mul_f32 v[2:3], v[6:7], v[6:7]
	v_add_f32_e32 v4, v13, v4
	v_add_f32_e32 v2, v2, v4
	v_add_f32_e32 v2, v3, v2
	s_waitcnt lgkmcnt(0)
	s_nop 1
	v_add_f32_dpp v2, v2, v2 quad_perm:[1,0,3,2] row_mask:0xf bank_mask:0xf
	s_nop 1
	v_add_f32_dpp v2, v2, v2 quad_perm:[2,3,0,1] row_mask:0xf bank_mask:0xf
	s_nop 1
	v_add_f32_dpp v2, v2, v2 row_half_mirror row_mask:0xf bank_mask:0xf
	s_nop 1
	v_add_f32_dpp v2, v2, v2 row_mirror row_mask:0xf bank_mask:0xf
	v_mov_b32_e32 v3, v2
	s_nop 1
	v_permlane16_swap_b32_e32 v2, v3
	v_add_f32_e32 v2, v2, v3
	v_mov_b32_e32 v3, v2
	s_nop 1
	v_permlane32_swap_b32_e32 v2, v3
	v_add_f32_e32 v2, v2, v3
	v_fmamk_f32 v2, v2, 0x3b000000, v231
	v_cmp_gt_f32_e32 vcc, s3, v2
	v_mul_f32_e32 v3, 0x4b800000, v2
	s_nop 0
	v_cndmask_b32_e32 v2, v2, v3, vcc
	v_rsq_f32_e32 v2, v2
	s_nop 0
	v_mul_f32_e32 v3, 0x45800000, v2
	v_cndmask_b32_e32 v10, v2, v3, vcc
	v_pk_mul_f32 v[2:3], v[38:39], v[10:11] op_sel_hi:[1,0]
	v_pk_mul_f32 v[0:1], v[0:1], v[10:11] op_sel_hi:[1,0]
	v_pk_mul_f32 v[2:3], v[22:23], v[2:3]
	v_pk_mul_f32 v[0:1], v[24:25], v[0:1]
	v_cvt_pk_bf16_f32 v2, v2, v3
	v_cvt_pk_bf16_f32 v3, v0, v1
	v_pk_mul_f32 v[0:1], v[8:9], v[10:11] op_sel_hi:[1,0]
	s_nop 0
	v_pk_mul_f32 v[0:1], v[18:19], v[0:1]
	s_nop 0
	v_cvt_pk_bf16_f32 v4, v0, v1
	v_pk_mul_f32 v[0:1], v[6:7], v[10:11] op_sel_hi:[1,0]
	s_nop 0
	v_pk_mul_f32 v[0:1], v[20:21], v[0:1]
	s_nop 0
	v_cvt_pk_bf16_f32 v5, v0, v1
	global_store_dwordx4 v[36:37], v[2:5], off offset:1024
	s_cmp_lg_u32 s25, 0
	s_cbranch_scc1 .Lgate_odd_rot
	s_waitcnt vmcnt(1)
.Lgate_odd_rot:
	s_nop 1
	v_mov_b64_e32 v[0:1], v[54:55]
	v_mov_b64_e32 v[2:3], v[56:57]
	v_mov_b64_e32 v[4:5], v[58:59]
	v_mov_b64_e32 v[6:7], v[60:61]
	v_mov_b64_e32 v[8:9], v[62:63]
	v_mov_b64_e32 v[10:11], v[64:65]
	v_mov_b64_e32 v[12:13], v[66:67]
	v_mov_b64_e32 v[14:15], v[68:69]
	v_mov_b64_e32 v[54:55], v[70:71]
	v_mov_b64_e32 v[56:57], v[72:73]
	v_mov_b64_e32 v[58:59], v[74:75]
	v_mov_b64_e32 v[60:61], v[76:77]
	v_mov_b64_e32 v[62:63], v[78:79]
	v_mov_b64_e32 v[64:65], v[80:81]
	v_mov_b64_e32 v[66:67], v[82:83]
	v_mov_b64_e32 v[68:69], v[84:85]
	v_mov_b64_e32 v[70:71], v[86:87]
	v_mov_b64_e32 v[72:73], v[88:89]
	v_mov_b64_e32 v[74:75], v[90:91]
	v_mov_b64_e32 v[76:77], v[92:93]
	v_mov_b64_e32 v[78:79], v[94:95]
	v_mov_b64_e32 v[80:81], v[96:97]
	v_mov_b64_e32 v[82:83], v[98:99]
	v_mov_b64_e32 v[84:85], v[100:101]
